# attention: static s_setprio 1 for waves 4-7 during the attention phase
# baseline (speedup 1.0000x reference)
.LBB0_1326:
	s_or_b64 exec, exec, s[0:1]
	s_waitcnt lgkmcnt(0)
	v_mov_b32_e32 v0, v226
	s_barrier
	v_readlane_b32 s4, v254, 30
	v_and_b32_e32 v0, 63, v0
	v_lshlrev_b32_e32 v0, 2, v0
	v_readlane_b32 s14, v254, 40
	v_readlane_b32 s15, v254, 41
	s_nop 4
	global_load_dword v1, v0, s[14:15]
	global_load_dword v2, v0, s[14:15] offset:256
	global_load_dword v3, v0, s[14:15] offset:512
	global_load_dword v4, v0, s[14:15] offset:768
	s_lshl_b32 s0, s84, 5
	s_and_b32 s0, s0, 0x380
	s_and_b32 s33, s84, 3
	s_and_b32 s40, s48, 0xe000
	s_lshl_b32 s4, s0, 1
	v_readlane_b32 s5, v254, 31
	s_add_u32 s42, s80, s4
	v_readlane_b32 s6, v254, 32
	s_addc_u32 s43, s81, 0
	s_lshl_b32 s5, s40, 11
	v_readlane_b32 s7, v254, 33
	s_add_u32 s6, s86, s5
	s_addc_u32 s7, s87, 0
	s_add_u32 s28, s6, s4
	s_addc_u32 s29, s7, 0
	s_add_u32 s5, s62, s5
	v_readlane_b32 s8, v254, 34
	v_readlane_b32 s9, v254, 35
	v_readlane_b32 s10, v254, 36
	v_readlane_b32 s11, v254, 37
	v_readlane_b32 s12, v254, 38
	v_readlane_b32 s13, v254, 39
	v_readlane_b32 s16, v254, 42
	v_readlane_b32 s17, v254, 43
	v_readlane_b32 s18, v254, 44
	v_readlane_b32 s19, v254, 45
	v_writelane_b32 v254, s62, 14
	s_addc_u32 s6, s63, 0
	s_mov_b64 s[10:11], s[14:15]
	s_add_u32 s30, s5, s4
	s_addc_u32 s31, s6, 0
	s_or_b32 s0, s0, 64
	v_writelane_b32 v254, s63, 15
	s_add_u32 s50, s90, s4
	s_addc_u32 s51, s91, 0
	s_mov_b32 s1, 0
	s_mov_b32 s24, 0xfffe0000
	v_mov_b32_e32 v213, 0
	s_mov_b64 s[12:13], 0x80
	s_mov_b64 s[14:15], 0x20000
	s_mov_b64 s[16:17], 0x40000
	s_mov_b64 s[18:19], 0x60000
	s_mov_b64 s[20:21], 0x20080
	s_mov_b64 s[22:23], 0xa0000
	s_mov_b32 s25, -1
	s_mov_b32 s41, 0x41000000
	s_mov_b64 s[26:27], 0x80000
	v_mov_b32_e32 v227, 0x3727c5ac
	v_mov_b32_e32 v228, 0xff800000
	s_mov_b32 s88, s1
	s_waitcnt vmcnt(2)
	v_mul_f32_e32 v0, v1, v2
	s_nop 1
	v_mov_b32_dpp v0, v0 quad_perm:[1,0,3,2] row_mask:0xf bank_mask:0xf bound_ctrl:1
	s_waitcnt vmcnt(0)
	v_mul_f32_e32 v5, v3, v4
	v_fmac_f32_e32 v0, v1, v2
	s_nop 0
	v_mov_b32_dpp v5, v5 quad_perm:[1,0,3,2] row_mask:0xf bank_mask:0xf bound_ctrl:1
	v_fmac_f32_e32 v5, v3, v4
	v_add_f32_dpp v0, v0, v0 quad_perm:[2,3,0,1] row_mask:0xf bank_mask:0xf bound_ctrl:1
	s_nop 0
	v_add_f32_dpp v1, v5, v5 quad_perm:[2,3,0,1] row_mask:0xf bank_mask:0xf bound_ctrl:1
	v_add_f32_dpp v0, v0, v0 row_half_mirror row_mask:0xf bank_mask:0xf bound_ctrl:1
	s_nop 0
	v_add_f32_dpp v1, v1, v1 row_half_mirror row_mask:0xf bank_mask:0xf bound_ctrl:1
	v_add_f32_dpp v0, v0, v0 row_mirror row_mask:0xf bank_mask:0xf bound_ctrl:1
	s_nop 0
	v_add_f32_dpp v1, v1, v1 row_mirror row_mask:0xf bank_mask:0xf bound_ctrl:1
	v_readlane_b32 s6, v0, 16
	v_readlane_b32 s8, v0, 48
	v_readlane_b32 s10, v1, 16
	v_readlane_b32 s34, v1, 48
	v_readlane_b32 s5, v0, 0
	v_readlane_b32 s7, v0, 32
	v_readlane_b32 s9, v1, 0
	v_readlane_b32 s11, v1, 32
	v_mov_b32_e32 v0, s6
	v_mov_b32_e32 v1, s8
	v_mov_b32_e32 v2, s10
	v_mov_b32_e32 v3, s34
	v_add_f32_e32 v0, s5, v0
	v_add_f32_e32 v1, s7, v1
	v_add_f32_e32 v2, s9, v2
	v_add_f32_e32 v3, s11, v3
	v_add_f32_e32 v0, v0, v1
	v_add_f32_e32 v1, v2, v3
	v_mul_f32_e32 v0, 0x3fb8aa3b, v0
	v_mul_f32_e32 v1, 0x3fb8aa3b, v1
	v_exp_f32_e32 v0, v0
	v_exp_f32_e32 v1, v1
	v_readlane_b32 s6, v254, 62
	v_readlane_b32 s7, v254, 63
	s_add_u32 s52, s6, s4
	v_sub_f32_e32 v0, v0, v1
	s_addc_u32 s72, s7, 0
	s_lshl_b32 s0, s0, 1
	v_add_f32_e32 v229, 0x3eb60549, v0
	v_readfirstlane_b32 s4, v226
	s_lshr_b32 s4, s4, 6
	s_cmp_lt_u32 s4, 4
	s_cbranch_scc1 .Lattn_prio_skip
	s_setprio 1
.Lattn_prio_skip:
	s_branch .LBB0_1328

.LBB0_1488:
	s_setprio 0
	s_waitcnt vmcnt(0)
	v_readlane_b32 s58, v254, 8
	v_readlane_b32 s59, v254, 9
	s_barrier
	s_and_saveexec_b64 s[0:1], s[58:59]
	v_readlane_b32 s56, v254, 14
	v_readlane_b32 s57, v254, 15
	s_cbranch_execz .LBB0_1540
	s_add_i32 s4, 0, 0x27fc0
	v_mov_b32_e32 v0, s4
	s_waitcnt vmcnt(0) expcnt(0) lgkmcnt(0)
	ds_read_b32 v2, v0
	s_add_i32 s4, 0, 0x27fc4
	v_mov_b32_e32 v0, s4
	ds_read_b32 v0, v0
	s_waitcnt lgkmcnt(1)
	v_cmp_ne_u32_e32 vcc, 0, v2
	s_cbranch_vccnz .LBB0_1504
	s_add_u32 s6, s92, 0x1200
	s_addc_u32 s7, s93, 0
	s_add_u32 s8, s92, 0x1400
	s_addc_u32 s9, s93, 0
	s_add_u32 s10, s92, 0x1500
	s_addc_u32 s11, s93, 0
	s_add_u32 s12, s92, 0x1600
	s_addc_u32 s13, s93, 0
	s_add_u32 s14, s92, 0x1700
	s_addc_u32 s15, s93, 0
	s_add_u32 s16, s92, 0x1800
	s_addc_u32 s17, s93, 0
	s_add_u32 s18, s92, 0x1900
	s_addc_u32 s19, s93, 0
	s_add_u32 s20, s92, 0x1a00
	s_addc_u32 s21, s93, 0
	s_add_u32 s22, s92, 0x1b00
	s_addc_u32 s23, s93, 0
	s_add_u32 s24, s92, 0x1c00
	s_addc_u32 s25, s93, 0
	s_add_u32 s26, s92, 0x1d00
	s_addc_u32 s27, s93, 0
	s_add_u32 s28, s92, 0x1e00
	s_addc_u32 s29, s93, 0
	s_add_u32 s30, s92, 0x1f00
	v_readlane_b32 s4, v254, 10
	s_addc_u32 s31, s93, 0
	s_mul_i32 s33, s95, s4
	s_add_u32 s4, s92, 0x2000
	s_addc_u32 s5, s93, 0
	s_add_u32 s34, s92, 0x2100
	s_addc_u32 s35, s93, 0
	s_add_u32 s36, s92, 0x2200
	s_addc_u32 s37, s93, 0
	s_add_u32 s38, s92, 0x2300
	s_mul_i32 s33, s33, s94
	s_addc_u32 s39, s93, 0
	s_mov_b32 s46, 1
	v_mov_b32_e32 v16, 0
	s_branch .LBB0_1492
